# conv strip loops: loop-head wait no longer drains the previous trip's stores
# baseline (speedup 1.0000x reference)
; __device__ __forceinline__ void ffn_conv_item(int tid_in, int b, int strip, bf16_t* h1, const bf16_t* h2, const float* cw, const float* cb, bool st = true) {
;     ...
;     const size_t off0 = ((size_t)b * SEQL + 512 * wid) * 5632 + ch;
;     u32x4 pg = {0u, 0u, 0u, 0u}, pv = {0u, 0u, 0u, 0u};
;     if (wid > 0) { pg = *(const u32x4*)(h1 + off0 + (ptrdiff_t)(rl - 8) * 5632); pv = *(const u32x4*)(h2 + off0 + (ptrdiff_t)(rl - 8) * 5632); }
;     asm volatile("s_waitcnt vmcnt(0)" ::: "memory");
;     __syncthreads();
;     u32x4 cg4[4], cv4[4];
; #pragma unroll
;     for (int j = 0; j < 4; ++j) { cg4[j] = __builtin_nontemporal_load((const u32x4*)(h1 + off0 + (size_t)(8 * j + rl) * 5632)); cv4[j] = __builtin_nontemporal_load((const u32x4*)(h2 + off0 + (size_t)(8 * j + rl) * 5632)); }
.LBB0_23:
	v_lshlrev_b64 v[70:71], 1, v[0:1]
	v_lshl_add_u64 v[36:37], v[36:37], 0, v[70:71]
	v_lshl_add_u64 v[34:35], v[34:35], 0, v[70:71]
	v_add_co_u32_e32 v70, vcc, 0x16000, v36
	s_waitcnt vmcnt(0)
	s_nop 1
	v_addc_co_u32_e32 v71, vcc, 0, v37, vcc
	v_add_co_u32_e32 v72, vcc, 0x16000, v34
	s_barrier
	s_nop 0
	v_addc_co_u32_e32 v73, vcc, 0, v35, vcc
	global_load_dwordx4 v[94:97], v[36:37], off nt
	global_load_dwordx4 v[98:101], v[34:35], off nt
	global_load_dwordx4 v[82:85], v[70:71], off nt
	global_load_dwordx4 v[86:89], v[72:73], off nt
	v_add_co_u32_e32 v70, vcc, 0x2c000, v36
	v_and_b32_e32 v107, 64, v220
	s_nop 0
	v_addc_co_u32_e32 v71, vcc, 0, v37, vcc
	v_add_co_u32_e32 v72, vcc, 0x2c000, v34
	v_add_u32_e32 v0, 56, v106
	s_nop 0
	v_addc_co_u32_e32 v73, vcc, 0, v35, vcc
	v_add_co_u32_e32 v36, vcc, 0x42000, v36
	global_load_dwordx4 v[74:77], v[70:71], off nt
	global_load_dwordx4 v[78:81], v[72:73], off nt
	v_addc_co_u32_e32 v37, vcc, 0, v37, vcc
	v_add_co_u32_e32 v70, vcc, 0x42000, v34
	v_add_u32_e32 v106, 48, v106
	s_nop 0
	v_addc_co_u32_e32 v71, vcc, 0, v35, vcc
	global_load_dwordx4 v[34:37], v[36:37], off nt
	s_nop 0
	global_load_dwordx4 v[70:73], v[70:71], off nt
	s_movk_i32 s9, 0x2c00
	v_and_or_b32 v0, v0, 63, v107
	v_and_or_b32 v106, v106, 63, v107
	s_waitcnt vmcnt(20)
	v_mov_b32_e32 v136, v38
	v_mov_b32_e32 v137, v6
	v_mov_b32_e32 v6, v39
	v_mad_u64_u32 v[38:39], s[18:19], v140, s9, v[138:139]
	v_cmp_eq_u32_e64 s[40:41], 7, v140
	v_lshlrev_b32_e32 v0, 2, v0
	v_cmp_gt_u32_e64 s[42:43], 6, v140
	v_lshlrev_b32_e32 v147, 2, v106
	s_waitcnt vmcnt(9)
	v_mov_b32_e32 v106, v68
	v_mov_b32_e32 v107, v28
	v_mov_b32_e32 v108, v64
	v_mov_b32_e32 v109, v20
	v_mov_b32_e32 v110, v60
	v_mov_b32_e32 v111, v12
	v_mov_b32_e32 v112, v56
	v_mov_b32_e32 v113, v4
	v_mov_b32_e32 v28, v69
	v_mov_b32_e32 v20, v65
	v_mov_b32_e32 v12, v61
	v_mov_b32_e32 v4, v57
	v_mov_b32_e32 v114, v66
	v_mov_b32_e32 v115, v26
	v_mov_b32_e32 v116, v62
	v_mov_b32_e32 v117, v18
	v_mov_b32_e32 v118, v58
	v_mov_b32_e32 v119, v10
	v_mov_b32_e32 v120, v54
	v_mov_b32_e32 v121, v2
	v_mov_b32_e32 v26, v67
	v_mov_b32_e32 v18, v63
	v_mov_b32_e32 v10, v59
	v_mov_b32_e32 v2, v55
	s_waitcnt vmcnt(8)
	v_mov_b32_e32 v122, v52
	v_mov_b32_e32 v123, v32
	v_mov_b32_e32 v124, v48
	v_mov_b32_e32 v125, v24
	v_mov_b32_e32 v126, v44
	v_mov_b32_e32 v127, v16
	v_mov_b32_e32 v128, v40
	v_mov_b32_e32 v129, v8
	v_mov_b32_e32 v32, v53
	v_mov_b32_e32 v24, v49
	v_mov_b32_e32 v16, v45
	v_mov_b32_e32 v8, v41
	v_mov_b32_e32 v130, v50
	v_mov_b32_e32 v131, v30
	v_mov_b32_e32 v132, v46
	v_mov_b32_e32 v133, v22
	v_mov_b32_e32 v134, v42
	v_mov_b32_e32 v135, v14
	v_mov_b32_e32 v30, v51
	v_mov_b32_e32 v22, v47
	v_mov_b32_e32 v14, v43
	v_lshl_add_u64 v[138:139], s[66:67], 0, v[38:39]
	s_mov_b64 s[34:35], 0
	s_waitcnt vmcnt(0)
	s_branch .LBB0_25

; __device__ __forceinline__ void ffn_conv_item(int tid_in, int b, int strip, bf16_t* h1, const bf16_t* h2, const float* cw, const float* cb, bool st = true) {
;     ...
;     for (int blk = 0; blk < 16; ++blk) {
;         u32x4 ng4[4], nv4[4];
;         if (blk + 1 < 16) {
; #pragma unroll
;             for (int j = 0; j < 4; ++j) { const size_t o_ = off0 + (size_t)(32 * (blk + 1) + 8 * j + rl) * 5632; ng4[j] = __builtin_nontemporal_load((const u32x4*)(h1 + o_)); nv4[j] = __builtin_nontemporal_load((const u32x4*)(h2 + o_)); }
;         }
;     ...
;         for (int j = 0; j < 4; ++j) { cg4[j] = ng4[j]; cv4[j] = nv4[j]; }
.LBB0_25:
	s_waitcnt vmcnt(4)
	v_mov_b64_e32 v[48:49], v[36:37]
	v_mov_b64_e32 v[46:47], v[34:35]
	s_cmp_eq_u32 s34, 0x528000
	v_lshl_add_u64 v[140:141], v[138:139], 0, s[34:35]
	s_cbranch_scc1 .LBB0_24
	v_add_co_u32_e32 v34, vcc, 0x4a58000, v140
	s_nop 1
	v_addc_co_u32_e32 v35, vcc, 0, v141, vcc
	v_add_co_u32_e32 v36, vcc, 0xfa58000, v140
	s_nop 1
	v_addc_co_u32_e32 v37, vcc, 0, v141, vcc
	global_load_dwordx4 v[38:41], v[34:35], off nt
	global_load_dwordx4 v[42:45], v[36:37], off nt
	v_add_co_u32_e32 v34, vcc, 0x4a6e000, v140
	s_nop 1
	v_addc_co_u32_e32 v35, vcc, 0, v141, vcc
	v_add_co_u32_e32 v36, vcc, 0xfa6e000, v140
	s_nop 1
	v_addc_co_u32_e32 v37, vcc, 0, v141, vcc
	global_load_dwordx4 v[50:53], v[34:35], off nt
	global_load_dwordx4 v[54:57], v[36:37], off nt
	v_add_co_u32_e32 v34, vcc, 0x4a84000, v140
	s_nop 1
	v_addc_co_u32_e32 v35, vcc, 0, v141, vcc
	v_add_co_u32_e32 v36, vcc, 0xfa84000, v140
	s_nop 1
	v_addc_co_u32_e32 v37, vcc, 0, v141, vcc
	global_load_dwordx4 v[58:61], v[34:35], off nt
	global_load_dwordx4 v[62:65], v[36:37], off nt
	v_add_co_u32_e32 v34, vcc, 0x4a9a000, v140
	s_nop 1
	v_addc_co_u32_e32 v35, vcc, 0, v141, vcc
	v_add_co_u32_e32 v66, vcc, 0xfa9a000, v140
	s_nop 1
	v_addc_co_u32_e32 v67, vcc, 0, v141, vcc
	global_load_dwordx4 v[34:37], v[34:35], off nt
	s_nop 0
	global_load_dwordx4 v[66:69], v[66:67], off nt
	s_branch .LBB0_24
	s_nop 0
	s_nop 0
	s_nop 0
	s_nop 0
	s_nop 0
	s_nop 0
	s_nop 0
	s_nop 0
	s_nop 0
	s_nop 0
	s_nop 0
	s_nop 0
	s_nop 0
	s_nop 0
	s_nop 0
	s_nop 0
	s_nop 0
	s_nop 0
	s_nop 0
	s_nop 0
	s_nop 0
	s_nop 0
	s_nop 0
	s_nop 0
	s_nop 0
	s_nop 0
	s_nop 0
	s_nop 0
	s_nop 0
	s_nop 0
	s_nop 0
	s_nop 0
	s_nop 0
	s_nop 0
	s_nop 0
	s_nop 0
	s_nop 0
	s_nop 0
	s_nop 0
	s_nop 0
	s_nop 0
	s_nop 0
	s_nop 0
	s_nop 0
	s_nop 0
	s_nop 0
	s_nop 0
	s_nop 0
	s_nop 0
	s_nop 0
	s_nop 0
	s_nop 0
	s_nop 0
	s_nop 0
	s_nop 0
	s_nop 0
	s_nop 0
	s_nop 0
	s_nop 0
	s_nop 0
	s_nop 0
	s_nop 0
	s_nop 0
	s_nop 0
	s_nop 0
	s_nop 0
	s_nop 0
	s_nop 0
	s_nop 0
	s_nop 0
	s_nop 0
	s_nop 0
	s_nop 0
	s_nop 0
	s_nop 0
	s_nop 0
	s_nop 0
	s_nop 0
	s_nop 0
	s_nop 0
	s_nop 0
	s_nop 0
	s_nop 0
	s_nop 0
	s_nop 0
	s_nop 0
	s_nop 0
	s_nop 0
	s_nop 0
	s_nop 0
	s_nop 0
	s_nop 0
	s_nop 0
	s_nop 0
	s_nop 0
	s_nop 0
	s_nop 0
	s_nop 0
	s_nop 0
	s_nop 0
	s_nop 0
	s_nop 0
	s_nop 0
	s_nop 0
	s_nop 0
	s_nop 0
	s_nop 0
	s_nop 0
	s_nop 0
	s_nop 0
	s_nop 0
	s_nop 0
	s_nop 0
	s_nop 0
	s_nop 0
	s_nop 0
	s_nop 0
	s_nop 0
	s_nop 0
	s_nop 0
	s_nop 0
	s_nop 0
	s_nop 0
	s_nop 0
	s_nop 0
	s_nop 0
	s_nop 0
	s_nop 0
	s_nop 0
	s_nop 0
	s_nop 0
	s_nop 0
	s_nop 0
	s_nop 0
	s_nop 0
	s_nop 0
	s_nop 0
	s_nop 0
	s_nop 0
	s_nop 0
	s_nop 0
	s_nop 0
	s_nop 0
	s_nop 0
	s_nop 0
	s_nop 0
	s_nop 0
	s_nop 0
	s_nop 0
	s_nop 0
	s_nop 0
	s_nop 0
	s_nop 0
	s_nop 0
	s_nop 0
	s_nop 0
	s_nop 0
	s_nop 0
	s_nop 0
	s_nop 0
	s_nop 0
	s_nop 0
	s_nop 0
	s_nop 0
	s_nop 0
	s_nop 0
	s_nop 0
	s_nop 0
	s_nop 0
	s_nop 0
	s_nop 0
	s_nop 0
	s_nop 0
	s_nop 0
	s_nop 0
	s_nop 0
	s_nop 0
	s_nop 0
	s_nop 0
	s_nop 0
	s_nop 0
	s_nop 0
	s_nop 0
	s_nop 0
	s_nop 0
	s_nop 0
	s_nop 0
	s_nop 0
	s_nop 0
	s_nop 0
	s_nop 0
	s_nop 0
	s_nop 0
	s_nop 0
	s_nop 0
	s_nop 0
	s_nop 0
	s_nop 0
	s_nop 0
	s_nop 0
	s_nop 0
	s_nop 0
	s_nop 0
	s_nop 0
	s_nop 0
	s_nop 0
	s_nop 0
	s_nop 0
	s_nop 0
	s_nop 0
	s_nop 0
	s_nop 0
	s_nop 0
	s_nop 0
	s_nop 0
	s_nop 0
	s_nop 0
	s_nop 0
	s_nop 0
	s_nop 0
	s_nop 0
	s_nop 0
	s_nop 0
	s_nop 0
	s_nop 0
	s_nop 0
	s_nop 0
	s_nop 0
	s_nop 0
	s_nop 0
	s_nop 0
	s_nop 0
	s_nop 0
	s_nop 0
	s_nop 0
	s_nop 0
	s_nop 0
	s_nop 0
	s_nop 0
	s_nop 0
	s_nop 0
	s_nop 0
	s_nop 0
	s_nop 0
	s_nop 0
	s_nop 0
	s_nop 0
	s_nop 0
	s_nop 0
	s_nop 0
	s_nop 0
	s_nop 0
	s_nop 0
	s_nop 0
	s_nop 0
	s_nop 0
	s_nop 0
	s_nop 0
	s_nop 0
	s_nop 0
	s_nop 0
	s_nop 0
	s_nop 0
	s_nop 0
	s_nop 0
	s_nop 0
	s_nop 0
	s_nop 0
	s_nop 0
	s_nop 0
	s_nop 0
	s_nop 0
	s_nop 0
	s_nop 0
	s_nop 0
	s_nop 0
	s_nop 0
	s_nop 0
	s_nop 0
	s_nop 0
	s_nop 0
	s_nop 0
	s_nop 0
	s_nop 0
	s_nop 0
	s_nop 0
	s_nop 0
	s_nop 0
	s_nop 0
	s_nop 0
	s_nop 0
	s_nop 0
	s_nop 0
	s_nop 0
	s_nop 0
	s_nop 0
	s_nop 0
	s_nop 0
	s_nop 0
	s_nop 0
	s_nop 0
	s_nop 0
	s_nop 0
	s_nop 0
	s_nop 0
	s_nop 0
	s_nop 0
	s_nop 0
	s_nop 0
	s_nop 0
	s_nop 0
	s_nop 0
	s_nop 0
	s_nop 0
	s_nop 0
	s_nop 0
	s_nop 0
	s_nop 0
	s_nop 0
	s_nop 0
	s_nop 0
	s_nop 0
	s_nop 0
	s_nop 0
	s_nop 0
	s_nop 0
	s_nop 0
	s_nop 0
	s_nop 0
	s_nop 0
	s_nop 0
	s_nop 0
	s_nop 0
	s_nop 0
	s_nop 0
	s_nop 0
	s_nop 0
	s_nop 0
	s_nop 0
	s_nop 0
	s_nop 0
	s_nop 0
	s_nop 0
	s_nop 0
	s_nop 0
	s_nop 0
	s_nop 0
	s_nop 0
	s_nop 0
	s_nop 0
	s_nop 0
	s_nop 0
	s_nop 0
	s_nop 0
	s_nop 0
	s_nop 0
	s_nop 0
	s_nop 0
	s_nop 0
	s_nop 0
	s_nop 0
	s_nop 0
	s_nop 0
	s_nop 0
	s_nop 0
	s_nop 0
	s_nop 0
	s_nop 0
	s_nop 0
	s_nop 0
	s_nop 0
	s_nop 0
	s_nop 0
	s_nop 0
	s_nop 0
	s_nop 0
	s_nop 0
	s_nop 0
	s_nop 0
	s_nop 0
	s_nop 0
	s_nop 0
	s_nop 0
	s_nop 0
	s_nop 0
	s_nop 0
	s_nop 0
	s_nop 0
	s_nop 0
	s_nop 0
	s_nop 0
	s_nop 0
	s_nop 0
	s_nop 0
	s_nop 0
	s_nop 0
	s_nop 0
	s_nop 0
	s_nop 0
	s_nop 0
	s_nop 0
	s_nop 0
	s_nop 0
	s_nop 0
	s_nop 0
	s_nop 0
	s_nop 0
	s_nop 0
	s_nop 0
	s_nop 0
	s_nop 0
	s_nop 0
	s_nop 0
	s_nop 0
	s_nop 0
	s_nop 0
	s_nop 0
	s_nop 0
	s_nop 0
	s_nop 0
	s_nop 0
	s_nop 0
	s_nop 0
	s_nop 0
	s_nop 0
	s_nop 0
	s_nop 0
	s_nop 0
	s_nop 0
	s_nop 0
	s_nop 0
	s_nop 0
	s_nop 0
	s_nop 0
	s_nop 0
	s_nop 0
	s_nop 0
	s_nop 0
	s_nop 0
	s_nop 0
	s_nop 0
	s_nop 0
	s_nop 0
	s_nop 0
	s_nop 0
	s_nop 0
	s_nop 0
	s_nop 0
	s_nop 0
	s_nop 0
	s_nop 0
	s_nop 0
	s_nop 0
	s_nop 0
	s_nop 0
	s_nop 0
	s_nop 0
	s_nop 0
	s_nop 0
	s_nop 0
	s_nop 0
	s_nop 0
	s_nop 0
	s_nop 0
	s_nop 0
	s_nop 0
	s_nop 0
	s_nop 0
	s_nop 0
	s_nop 0
	s_nop 0
	s_nop 0
	s_nop 0
	s_nop 0
	s_nop 0
	s_nop 0
	s_nop 0
	s_nop 0
	s_nop 0
	s_nop 0
	s_nop 0
	s_nop 0
	s_nop 0
	s_nop 0
	s_nop 0
	s_nop 0
	s_nop 0
	s_nop 0
	s_nop 0
	s_nop 0
	s_nop 0
	s_nop 0
	s_nop 0
	s_nop 0
	s_nop 0
	s_nop 0
	s_nop 0
	s_nop 0
	s_nop 0
	s_nop 0
	s_nop 0
	s_nop 0
	s_nop 0
	s_nop 0
	s_nop 0
	s_nop 0
	s_nop 0
	s_nop 0
	s_nop 0
	s_nop 0

; __device__ __forceinline__ void qk_conv_item(int tid_in, int b, int strip, bf16_t* z1, const float* conv_qk) {
;     ...
;     const float qs = (ch < 1024) ? 0.08838834764831845f : 1.f;
;     bf16_t* base = z1 + ((size_t)b * SEQL + 512 * wid) * Z1_LD + 1280 + ch;
;     u32x4 prev = {0u, 0u, 0u, 0u};
;     if (wid > 0) prev = *(const u32x4*)(base + (ptrdiff_t)(rl - 8) * Z1_LD);
;     asm volatile("s_waitcnt vmcnt(0)" ::: "memory");
;     __syncthreads();
;     u32x4 cur4[4];
; #pragma unroll
;     for (int j = 0; j < 4; ++j) cur4[j] = *(const u32x4*)(base + (size_t)(8 * j + rl) * Z1_LD);
.LBB0_882:
	v_lshl_add_u64 v[18:19], v[18:19], 0, v[0:1]
	s_mov_b32 s17, 0xd000
	v_add_co_u32_e32 v20, vcc, s17, v18
	s_mov_b32 s17, 0x1a000
	s_nop 0
	v_addc_co_u32_e32 v21, vcc, 0, v19, vcc
	s_waitcnt vmcnt(0)
	s_barrier
	global_load_dwordx4 v[46:49], v[18:19], off offset:2560
	global_load_dwordx4 v[42:45], v[20:21], off offset:2560
	v_add_co_u32_e32 v20, vcc, s17, v18
	s_mov_b32 s17, 0x27000
	s_nop 0
	v_addc_co_u32_e32 v21, vcc, 0, v19, vcc
	v_add_co_u32_e32 v18, vcc, s17, v18
	s_and_b32 s17, s9, 31
	s_nop 0
	v_addc_co_u32_e32 v19, vcc, 0, v19, vcc
	global_load_dwordx4 v[38:41], v[20:21], off offset:2560
	s_nop 0
	global_load_dwordx4 v[18:21], v[18:19], off offset:2560
	s_cmp_lt_u32 s16, 16
	s_cselect_b64 vcc, -1, 0
	v_mov_b32_e32 v0, 0x3db504f3
	v_cndmask_b32_e32 v77, 1.0, v0, vcc
	v_and_b32_e32 v0, 64, v220
	v_add_u32_e32 v55, 56, v54
	v_and_or_b32 v55, v55, 63, v0
	s_mul_hi_i32 s16, s6, 0x1a00000
	s_mul_i32 s6, s6, 0x1a00000
	s_mul_hi_i32 s18, s7, 0x1a00
	s_mulk_i32 s7, 0x1a00
	v_lshlrev_b32_e32 v78, 2, v55
	v_add_u32_e32 v55, 48, v54
	v_add_u32_e32 v54, 40, v54
	s_add_u32 s6, s6, s7
	v_and_or_b32 v55, v55, 63, v0
	v_and_or_b32 v0, v54, 63, v0
	s_addc_u32 s7, s16, s18
	v_lshlrev_b32_e32 v80, 2, v0
	s_waitcnt vmcnt(9)
	v_mov_b32_e32 v66, v22
	v_mov_b32_e32 v67, v6
	v_mov_b32_e32 v6, v23
	v_mov_b64_e32 v[22:23], s[6:7]
	v_lshlrev_b32_e32 v0, 1, v70
	v_mad_u64_u32 v[22:23], s[6:7], v71, s69, v[22:23]
	v_lshl_or_b32 v0, s17, 7, v0
	v_lshl_add_u64 v[22:23], v[22:23], 0, v[0:1]
	v_cmp_eq_u32_e64 s[40:41], 7, v71
	v_cmp_gt_u32_e64 s[42:43], 6, v71
	v_lshlrev_b32_e32 v79, 2, v55
	v_cmp_gt_u32_e64 s[44:45], 5, v71
	s_waitcnt vmcnt(8)
	v_mov_b32_e32 v54, v32
	v_mov_b32_e32 v55, v4
	v_mov_b32_e32 v4, v33
	s_waitcnt vmcnt(4)
	v_mov_b32_e32 v56, v36
	v_mov_b32_e32 v57, v16
	v_mov_b32_e32 v16, v37
	v_mov_b32_e32 v58, v30
	v_mov_b32_e32 v59, v2
	v_mov_b32_e32 v2, v31
	v_mov_b32_e32 v60, v34
	v_mov_b32_e32 v61, v14
	v_mov_b32_e32 v14, v35
	v_mov_b32_e32 v62, v24
	v_mov_b32_e32 v63, v8
	v_mov_b32_e32 v8, v25
	v_mov_b32_e32 v64, v28
	v_mov_b32_e32 v65, v12
	v_mov_b32_e32 v12, v29
	v_mov_b32_e32 v68, v26
	v_mov_b32_e32 v69, v10
	v_mov_b32_e32 v10, v27
	v_lshl_add_u64 v[70:71], s[66:67], 0, v[22:23]
	s_mov_b64 s[6:7], 0
	s_waitcnt vmcnt(0)
	s_branch .LBB0_884

; __device__ __forceinline__ void qk_conv_item(int tid_in, int b, int strip, bf16_t* z1, const float* conv_qk) {
;     ...
;     for (int blk = 0; blk < 16; ++blk) {
;         u32x4 nxt4[4];
;         if (blk + 1 < 16) {
; #pragma unroll
;             for (int j = 0; j < 4; ++j) nxt4[j] = *(const u32x4*)(base + (size_t)(32 * (blk + 1) + 8 * j + rl) * Z1_LD);
;         }
;     ...
;         for (int j = 0; j < 4; ++j) cur4[j] = nxt4[j];
.LBB0_884:
	s_waitcnt vmcnt(4)
	v_mov_b64_e32 v[24:25], v[20:21]
	v_mov_b64_e32 v[22:23], v[18:19]
	s_cmp_eq_u32 s6, 0x30c000
	v_lshl_add_u64 v[72:73], v[70:71], 0, s[6:7]
	s_cbranch_scc1 .LBB0_883
	v_add_co_u32_e32 v18, vcc, 0x6034000, v72
	s_nop 1
	v_addc_co_u32_e32 v19, vcc, 0, v73, vcc
	v_add_co_u32_e32 v20, vcc, 0x6041000, v72
	s_nop 1
	v_addc_co_u32_e32 v21, vcc, 0, v73, vcc
	global_load_dwordx4 v[26:29], v[18:19], off offset:2560
	global_load_dwordx4 v[30:33], v[20:21], off offset:2560
	v_add_co_u32_e32 v18, vcc, 0x604e000, v72
	s_nop 1
	v_addc_co_u32_e32 v19, vcc, 0, v73, vcc
	v_add_co_u32_e32 v20, vcc, 0x605b000, v72
	s_nop 1
	v_addc_co_u32_e32 v21, vcc, 0, v73, vcc
	global_load_dwordx4 v[34:37], v[18:19], off offset:2560
	s_nop 0
	global_load_dwordx4 v[18:21], v[20:21], off offset:2560
	s_branch .LBB0_883

; __global__ void __launch_bounds__(512, 2) mk_fwd(Args a_) {
;     ...
;         if (ph + 1 < ph_hi) { if (ph >= 1000) grid.sync(); else xcd_barrier(xbar); }
;     }
; }
.Lpost_getpc0:
	s_add_u32 s98, s98, (.LBB0_7-.Lpost_getpc0)&4294967295
	s_addc_u32 s99, s99, (.LBB0_7-.Lpost_getpc0)>>32
	s_setpc_b64 s[98:99]
	s_nop 0
	s_nop 0
	s_nop 0
	s_nop 0
	s_nop 0
	s_nop 0
	s_nop 0
	s_nop 0
	s_nop 0
	s_nop 0
	s_nop 0
	s_nop 0
	s_nop 0
	s_nop 0
	s_nop 0
	s_nop 0
	s_nop 0
	s_nop 0
	s_nop 0
	s_nop 0
	s_nop 0
	s_nop 0
	s_nop 0
	s_nop 0
	s_nop 0
	s_nop 0
	s_nop 0
	s_nop 0
	s_nop 0
	s_nop 0
	s_nop 0
	s_nop 0
	s_nop 0
	s_nop 0
	s_nop 0
	s_nop 0
	s_nop 0
	s_nop 0
	s_nop 0
	s_nop 0
	s_nop 0
	s_nop 0
	s_nop 0
	s_nop 0
	s_nop 0
	s_nop 0
	s_nop 0
	s_nop 0
	s_nop 0
	s_nop 0
	s_nop 0
	s_nop 0
	s_nop 0
	s_nop 0
	s_nop 0
	s_nop 0
	s_nop 0
	s_nop 0
	s_nop 0
	s_nop 0
	s_nop 0
	s_nop 0
	s_nop 0
	s_nop 0
	s_nop 0
	s_nop 0
	s_nop 0
	s_nop 0
	s_nop 0
	s_nop 0
	s_nop 0
	s_nop 0
	s_nop 0
	s_nop 0
	s_nop 0
	s_nop 0
	s_nop 0
	s_nop 0
	s_nop 0
	s_nop 0
	s_nop 0
	s_nop 0
	s_nop 0
	s_nop 0
	s_nop 0
	s_nop 0
	s_nop 0
	s_nop 0
	s_nop 0
	s_nop 0
	s_nop 0
	s_nop 0
	s_nop 0
	s_nop 0
	s_nop 0
	s_nop 0
	s_nop 0
	s_nop 0
	s_nop 0
	s_nop 0
	s_nop 0
	s_nop 0
	s_nop 0
	s_nop 0
	s_nop 0
	s_nop 0
	s_nop 0
	s_nop 0
	s_nop 0
	s_nop 0
	s_nop 0
	s_nop 0
	s_nop 0
	s_nop 0
	s_nop 0
	s_nop 0
	s_nop 0
	s_nop 0
	s_nop 0
	s_nop 0
	s_nop 0
	s_nop 0
	s_nop 0
	s_nop 0
	s_nop 0
	s_nop 0
	s_nop 0
	s_nop 0
	s_nop 0
	s_nop 0
	s_nop 0
	s_nop 0
	s_nop 0
	s_nop 0
	s_nop 0
	s_nop 0
	s_nop 0
	s_nop 0
	s_nop 0
	s_nop 0
	s_nop 0
	s_nop 0
	s_nop 0
	s_nop 0
	s_nop 0
	s_nop 0
	s_nop 0
	s_nop 0
	s_nop 0
	s_nop 0
	s_nop 0
	s_nop 0
	s_nop 0
	s_nop 0
	s_nop 0
	s_nop 0
	s_nop 0
	s_nop 0
	s_nop 0
	s_nop 0
	s_nop 0
	s_nop 0
	s_nop 0
	s_nop 0
	s_nop 0
	s_nop 0
	s_nop 0
	s_nop 0
	s_nop 0
	s_nop 0
	s_nop 0
	s_nop 0
	s_nop 0
	s_nop 0
	s_nop 0
	s_nop 0
	s_nop 0
	s_nop 0
	s_nop 0
	s_nop 0
	s_nop 0
	s_nop 0
	s_nop 0
	s_nop 0
	s_nop 0
	s_nop 0
	s_nop 0
	s_nop 0
	s_nop 0
	s_nop 0
	s_nop 0
	s_nop 0
	s_nop 0
	s_nop 0
	s_nop 0
	s_nop 0
	s_nop 0
	s_nop 0
	s_nop 0
	s_nop 0
	s_nop 0
	s_nop 0
	s_nop 0
	s_nop 0
	s_nop 0
	s_nop 0
	s_nop 0
	s_nop 0
	s_nop 0
	s_nop 0
	s_nop 0
	s_nop 0
	s_nop 0
	s_nop 0
	s_nop 0
	s_nop 0
	s_nop 0
	s_nop 0
	s_nop 0
	s_nop 0
	s_nop 0
	s_nop 0
	s_nop 0
	s_nop 0
	s_nop 0
	s_nop 0
	s_nop 0
	s_nop 0
	s_nop 0
	s_nop 0
	s_nop 0
	s_nop 0
	s_nop 0
	s_nop 0
	s_nop 0
	s_nop 0
	s_nop 0
	s_nop 0
	s_nop 0
	s_nop 0
	s_nop 0
	s_nop 0
	s_nop 0
	s_nop 0
	s_nop 0
	s_nop 0
	s_nop 0
	s_nop 0
	s_nop 0
	s_nop 0
	s_nop 0
	s_nop 0
	s_nop 0
	s_nop 0
	s_nop 0
	s_nop 0
	s_nop 0
	s_nop 0
	s_nop 0
	s_nop 0
	s_nop 0
	s_nop 0
	s_nop 0
	s_nop 0
	s_nop 0
	s_nop 0
	s_nop 0
	s_nop 0
	s_nop 0
	s_nop 0
	s_nop 0
	s_nop 0
	s_nop 0
	s_nop 0
	s_nop 0
	s_nop 0
	s_nop 0
	s_nop 0
	s_nop 0
	s_nop 0
	s_nop 0
	s_nop 0
	s_nop 0
	s_nop 0
	s_nop 0
	s_nop 0
	s_nop 0
	s_nop 0
	s_nop 0
	s_nop 0
	s_nop 0
	s_nop 0
	s_nop 0
	s_nop 0
	s_nop 0
	s_nop 0
	s_nop 0
	s_nop 0
	s_nop 0
	s_nop 0
	s_nop 0
	s_nop 0
	s_nop 0
	s_nop 0
	s_nop 0
	s_nop 0
	s_nop 0
	s_nop 0
	s_nop 0
	s_nop 0
	s_nop 0
	s_nop 0
	s_nop 0
	s_nop 0
	s_nop 0
	s_nop 0
	s_nop 0
	s_nop 0
	s_nop 0
	s_nop 0
	s_nop 0
	s_nop 0
	s_nop 0
	s_nop 0
	s_nop 0
	s_nop 0
	s_nop 0
	s_nop 0
	s_nop 0
	s_nop 0
	s_nop 0
	s_nop 0
	s_nop 0
	s_nop 0
	s_nop 0
	s_nop 0
	s_nop 0
	s_nop 0
	s_nop 0
	s_nop 0
	s_nop 0
	s_nop 0
	s_nop 0
	s_nop 0
	s_nop 0
	s_nop 0
	s_nop 0
	s_nop 0
	s_nop 0
	s_nop 0
	s_nop 0
	s_nop 0
	s_nop 0
	s_nop 0
	s_nop 0
	s_nop 0
	s_nop 0
	s_nop 0
	s_nop 0
	s_nop 0
	s_nop 0
	s_nop 0
	s_nop 0
	s_nop 0
	s_nop 0
	s_nop 0
	s_nop 0
	s_nop 0
	s_nop 0
	s_nop 0
	s_nop 0
	s_nop 0
	s_nop 0
	s_nop 0
	s_nop 0
	s_nop 0
	s_nop 0
	s_nop 0
	s_nop 0
	s_nop 0
	s_nop 0
	s_nop 0
	s_nop 0
	s_nop 0
	s_nop 0
	s_nop 0
	s_nop 0
	s_nop 0
	s_nop 0
	s_nop 0
	s_nop 0
	s_nop 0
	s_nop 0
	s_nop 0
	s_nop 0
	s_nop 0
	s_nop 0
	s_nop 0
	s_nop 0
	s_nop 0
	s_nop 0
	s_nop 0
	s_nop 0
	s_nop 0
	s_nop 0
	s_nop 0
	s_nop 0
	s_nop 0
	s_nop 0
	s_nop 0
	s_nop 0
	s_nop 0
	s_nop 0
	s_nop 0
	s_nop 0
	s_nop 0
	s_nop 0
	s_nop 0
	s_nop 0
	s_nop 0
	s_nop 0
	s_nop 0
	s_nop 0
	s_nop 0
	s_nop 0
	s_nop 0
	s_nop 0
	s_nop 0
	s_nop 0
	s_nop 0
	s_nop 0
	s_nop 0
	s_nop 0
	s_nop 0
	s_nop 0
	s_nop 0
	s_nop 0
	s_nop 0
	s_nop 0
	s_nop 0
	s_nop 0
	s_nop 0
	s_nop 0
	s_nop 0
	s_nop 0
	s_nop 0
	s_nop 0
	s_nop 0
	s_nop 0
	s_nop 0
	s_nop 0
	s_nop 0
	s_nop 0
	s_nop 0
	s_nop 0
	s_nop 0
	s_nop 0
	s_nop 0
	s_nop 0
	s_nop 0
	s_nop 0
	s_nop 0
	s_nop 0
	s_nop 0
	s_nop 0
	s_nop 0
	s_nop 0
	s_nop 0
	s_nop 0
	s_nop 0
	s_nop 0
	s_nop 0
	s_nop 0
	s_nop 0
	s_nop 0
	s_nop 0
	s_nop 0
	s_nop 0
	s_nop 0
	s_nop 0
	s_nop 0
	s_nop 0
	s_nop 0
	s_nop 0
	s_nop 0
	s_nop 0
	s_nop 0
	s_nop 0
	s_nop 0
	s_nop 0
	s_nop 0
	s_nop 0
	s_nop 0
	s_nop 0
	s_nop 0
	s_nop 0
	s_nop 0
	s_nop 0
.LBB0_1140:
	s_endpgm
